# mlstm_s (intra-chunk score phase): wave-0 gate prefix sum/max via DPP instead of 12 ds_bpermute round trips
# speedup vs baseline: 1.1435x; 1.0027x over previous
; __device__ __forceinline__ void phase_mlstm_s(const Ctx& c, int p, int l) {
;     ...
;             const int t = lane; float ig = -1e30f, lf = 0.f;
;             if (t < nvalid) { ig = gif[(size_t)(rbase + t) * 8 + h] + bi; const float gf = gif[(size_t)(rbase + t) * 8 + 4 + h] + bf; lf = fminf(gf, 0.f) - __logf(1.0f + __expf(-fabsf(gf))); }
;             float bc = lf;
; #pragma unroll
;             for (int o = 1; o < 64; o <<= 1) { const float u = __shfl_up(bc, o); if (lane >= o) bc += u; }
;             float cm = ig - bc;
; #pragma unroll
;             for (int o = 1; o < 64; o <<= 1) { const float u = __shfl_up(cm, o); if (lane >= o) cm = fmaxf(cm, u); }
;             bcum[t] = bc; igs[t] = ig; mloc[t] = bc + cm;
;         }
.LBB0_1097:
	s_or_b64 exec, exec, s[4:5]
	v_mov_b32_e32 v10, v1
	s_nop 1
	v_add_f32_dpp v10, v10, v10 row_shr:1 row_mask:0xf bank_mask:0xf
	s_nop 1
	v_add_f32_dpp v10, v10, v10 row_shr:2 row_mask:0xf bank_mask:0xf
	s_nop 1
	v_add_f32_dpp v10, v10, v10 row_shr:4 row_mask:0xf bank_mask:0xf
	s_nop 1
	v_add_f32_dpp v10, v10, v10 row_shr:8 row_mask:0xf bank_mask:0xf
	s_nop 1
	v_add_f32_dpp v10, v10, v10 row_bcast:15 row_mask:0xa bank_mask:0xf
	s_nop 1
	v_add_f32_dpp v10, v10, v10 row_bcast:31 row_mask:0xc bank_mask:0xf
	v_sub_f32_e32 v3, v0, v10
	s_nop 1
	v_max_f32_dpp v3, v3, v3 row_shr:1 row_mask:0xf bank_mask:0xf
	s_nop 1
	v_max_f32_dpp v3, v3, v3 row_shr:2 row_mask:0xf bank_mask:0xf
	s_nop 1
	v_max_f32_dpp v3, v3, v3 row_shr:4 row_mask:0xf bank_mask:0xf
	s_nop 1
	v_max_f32_dpp v3, v3, v3 row_shr:8 row_mask:0xf bank_mask:0xf
	s_nop 1
	v_max_f32_dpp v3, v3, v3 row_bcast:15 row_mask:0xa bank_mask:0xf
	s_nop 1
	v_max_f32_dpp v3, v3, v3 row_bcast:31 row_mask:0xc bank_mask:0xf
	v_lshlrev_b32_e32 v5, 2, v13
	v_add_u32_e32 v4, v9, v5
	v_add_u32_e32 v6, v8, v5
	ds_write_b32 v4, v0
	ds_write_b32 v6, v10
	v_add_f32_e32 v0, v10, v3
	v_add_u32_e32 v1, v16, v5
	ds_write_b32 v1, v0
